# v20 plus: one static s_setprio 1 for waves 4-7 for the duration of each attention unit (reset at the unit epilogue)
# speedup vs baseline: 1.0333x; 1.0062x over previous
; __device__ __forceinline__ unsigned cvt_pk_bf16(float lo, float hi) { unsigned r; asm volatile("v_cvt_pk_bf16_f32 %0, %1, %2" : "=v"(r) : "v"(lo), "v"(hi)); return r; }
; __device__ __forceinline__ int crow(int r, int hi) { return (r & 3) + 8 * (r >> 2) + 4 * hi; }
; __device__ __forceinline__ void attn_dense_body(const bf16_t* __restrict__ Qb, const bf16_t* __restrict__ Kh, const bf16_t* __restrict__ Vh, bf16_t* __restrict__ Ob, int seq, char* lds) {
;     ...
;   if (hi == 0) li_l[r32] = l_reg; asm volatile("s_waitcnt lgkmcnt(0)" ::: "memory");
;   float rli[16];
; #pragma unroll
;   for (int r = 0; r < 16; ++r) rli[r] = __builtin_amdgcn_rcpf(li_l[crow(r, hi)]);
;   bf16_t* Ow = Ob + (long)(wid * QBLK) * LDO;
; #pragma unroll
;   for (int r = 0; r < 16; ++r) { int orow = crow(r, hi);
;     for (int d0 = 0; d0 < 4; ++d0) Ow[(long)orow * LDO + d0 * 32 + r32] = (bf16_t)(cvt_pk_bf16(o[d0][r] * rli[r], 0.f) & 0xffffu); }
.LBB0_168:
	s_setprio 0
	s_or_b64 exec, exec, s[20:21]
	s_waitcnt lgkmcnt(0)
	v_add_u32_e32 v72, v210, v186
	ds_read_b128 v[64:67], v72
	ds_read_b128 v[68:71], v72 offset:32
	s_mul_i32 s21, s46, 0x1100
	s_mul_hi_i32 s20, s46, 0x1100
	s_add_u32 s21, s0, s21
	s_waitcnt lgkmcnt(1)
	v_rcp_f32_e32 v73, v64
	v_rcp_f32_e32 v74, v65
	v_rcp_f32_e32 v75, v66
	v_rcp_f32_e32 v76, v67
	ds_read_b128 v[64:67], v72 offset:64
	s_addc_u32 s22, s1, s20
	s_lshl_b32 s20, s28, 1
	s_add_u32 s20, s21, s20
	s_addc_u32 s21, s22, 0
	s_waitcnt lgkmcnt(1)
	v_rcp_f32_e32 v77, v68
	v_rcp_f32_e32 v78, v69
	v_rcp_f32_e32 v79, v70
	v_rcp_f32_e32 v80, v71
	ds_read_b128 v[68:71], v72 offset:96
	s_waitcnt lgkmcnt(1)
	v_rcp_f32_e32 v72, v64
	v_rcp_f32_e32 v81, v65
	v_mov_b64_e32 v[64:65], s[20:21]
	v_rcp_f32_e32 v82, v66
	v_rcp_f32_e32 v83, v67
	v_mad_i64_i32 v[64:65], s[20:21], v209, s84, v[64:65]
	v_lshlrev_b32_e32 v66, 1, v187
	v_mov_b32_e32 v67, v96
	v_lshl_add_u64 v[64:65], v[64:65], 0, v[66:67]
	v_mul_u32_u24_e32 v66, 0x4400, v97
	v_mul_f32_e32 v0, v0, v73
	v_lshl_add_u64 v[64:65], v[64:65], 0, v[66:67]
	v_cvt_pk_bf16_f32 v0, v0, v96
	global_store_short v[64:65], v0, off
	v_mul_f32_e32 v0, v48, v73
	v_cvt_pk_bf16_f32 v0, v0, v96
	global_store_short v[64:65], v0, off offset:64
	v_mul_f32_e32 v0, v32, v73
	v_cvt_pk_bf16_f32 v0, v0, v96
	global_store_short v[64:65], v0, off offset:128
	v_mul_f32_e32 v0, v16, v73
	v_cvt_pk_bf16_f32 v0, v0, v96
	global_store_short v[64:65], v0, off offset:192
	v_mul_f32_e32 v0, v1, v74
	s_movk_i32 s3, 0x1000
	v_cvt_pk_bf16_f32 v16, v0, v96
	v_add_co_u32_e32 v0, vcc, s3, v64
	s_movk_i32 s3, 0x2000
	s_nop 0
	v_addc_co_u32_e32 v1, vcc, 0, v65, vcc
	global_store_short v[0:1], v16, off offset:256
	v_mul_f32_e32 v16, v49, v74
	v_cvt_pk_bf16_f32 v16, v16, v96
	global_store_short v[0:1], v16, off offset:320
	v_mul_f32_e32 v16, v33, v74
	v_cvt_pk_bf16_f32 v16, v16, v96
	global_store_short v[0:1], v16, off offset:384
	v_mul_f32_e32 v16, v17, v74
	v_cvt_pk_bf16_f32 v16, v16, v96
	global_store_short v[0:1], v16, off offset:448
	v_mul_f32_e32 v0, v2, v75
	v_cvt_pk_bf16_f32 v2, v0, v96
	v_add_co_u32_e32 v0, vcc, s3, v64
	s_movk_i32 s20, 0x3000
	s_nop 0
	v_addc_co_u32_e32 v1, vcc, 0, v65, vcc
	global_store_short v[0:1], v2, off offset:512
	v_mul_f32_e32 v2, v50, v75
	v_cvt_pk_bf16_f32 v2, v2, v96
	global_store_short v[0:1], v2, off offset:576
	v_mul_f32_e32 v2, v34, v75
	v_cvt_pk_bf16_f32 v2, v2, v96
	global_store_short v[0:1], v2, off offset:640
	v_mul_f32_e32 v2, v18, v75
	v_cvt_pk_bf16_f32 v2, v2, v96
	global_store_short v[0:1], v2, off offset:704
	v_mul_f32_e32 v0, v3, v76
	v_cvt_pk_bf16_f32 v2, v0, v96
	v_add_co_u32_e32 v0, vcc, s20, v64
	s_mov_b32 s20, 0x8000
	s_nop 0
	v_addc_co_u32_e32 v1, vcc, 0, v65, vcc
	global_store_short v[0:1], v2, off offset:768
	v_mul_f32_e32 v2, v51, v76
	v_cvt_pk_bf16_f32 v2, v2, v96
	global_store_short v[0:1], v2, off offset:832
	v_mul_f32_e32 v2, v35, v76
	v_cvt_pk_bf16_f32 v2, v2, v96
	global_store_short v[0:1], v2, off offset:896
	v_mul_f32_e32 v2, v19, v76
	v_cvt_pk_bf16_f32 v2, v2, v96
	global_store_short v[0:1], v2, off offset:960
	v_mul_f32_e32 v0, v4, v77
	v_cvt_pk_bf16_f32 v2, v0, v96
	v_add_co_u32_e32 v0, vcc, s20, v64
	s_mov_b32 s20, 0x9000
	s_nop 0
	v_addc_co_u32_e32 v1, vcc, 0, v65, vcc
	global_store_short v[0:1], v2, off offset:2048
	v_mul_f32_e32 v2, v52, v77
	v_cvt_pk_bf16_f32 v2, v2, v96
	global_store_short v[0:1], v2, off offset:2112
	v_mul_f32_e32 v2, v36, v77
	v_cvt_pk_bf16_f32 v2, v2, v96
	global_store_short v[0:1], v2, off offset:2176
	v_mul_f32_e32 v2, v20, v77
	v_cvt_pk_bf16_f32 v2, v2, v96
	global_store_short v[0:1], v2, off offset:2240
	v_mul_f32_e32 v0, v5, v78
	v_cvt_pk_bf16_f32 v2, v0, v96
	v_add_co_u32_e32 v0, vcc, s20, v64
	s_mov_b32 s20, 0xa000
	s_nop 0
	v_addc_co_u32_e32 v1, vcc, 0, v65, vcc
	global_store_short v[0:1], v2, off offset:2304
	v_mul_f32_e32 v2, v53, v78
	v_cvt_pk_bf16_f32 v2, v2, v96
	global_store_short v[0:1], v2, off offset:2368
	v_mul_f32_e32 v2, v37, v78
	v_cvt_pk_bf16_f32 v2, v2, v96
	global_store_short v[0:1], v2, off offset:2432
	v_mul_f32_e32 v2, v21, v78
	v_cvt_pk_bf16_f32 v2, v2, v96
	global_store_short v[0:1], v2, off offset:2496
	v_mul_f32_e32 v0, v6, v79
	v_cvt_pk_bf16_f32 v2, v0, v96
	v_add_co_u32_e32 v0, vcc, s20, v64
	s_mov_b32 s3, 0xb000
	s_nop 0
	v_addc_co_u32_e32 v1, vcc, 0, v65, vcc
	global_store_short v[0:1], v2, off offset:2560
	v_mul_f32_e32 v2, v54, v79
	v_cvt_pk_bf16_f32 v2, v2, v96
	global_store_short v[0:1], v2, off offset:2624
	v_mul_f32_e32 v2, v38, v79
	v_cvt_pk_bf16_f32 v2, v2, v96
	global_store_short v[0:1], v2, off offset:2688
	v_mul_f32_e32 v2, v22, v79
	v_cvt_pk_bf16_f32 v2, v2, v96
	global_store_short v[0:1], v2, off offset:2752
	v_mul_f32_e32 v0, v7, v80
	v_cvt_pk_bf16_f32 v2, v0, v96
	v_add_co_u32_e32 v0, vcc, s3, v64
	s_mov_b32 s20, 0x11000
	s_nop 0
	v_addc_co_u32_e32 v1, vcc, 0, v65, vcc
	global_store_short v[0:1], v2, off offset:2816
	v_mul_f32_e32 v2, v55, v80
	v_cvt_pk_bf16_f32 v2, v2, v96
	global_store_short v[0:1], v2, off offset:2880
	v_mul_f32_e32 v2, v39, v80
	v_cvt_pk_bf16_f32 v2, v2, v96
	global_store_short v[0:1], v2, off offset:2944
	v_mul_f32_e32 v2, v23, v80
	v_cvt_pk_bf16_f32 v2, v2, v96
	global_store_short v[0:1], v2, off offset:3008
	v_mul_f32_e32 v0, v8, v72
	v_cvt_pk_bf16_f32 v2, v0, v96
	v_add_co_u32_e32 v0, vcc, s20, v64
	s_mov_b32 s3, 0x12000
	s_nop 0
	v_addc_co_u32_e32 v1, vcc, 0, v65, vcc
	global_store_short v[0:1], v2, off
	v_mul_f32_e32 v2, v56, v72
	v_cvt_pk_bf16_f32 v2, v2, v96
	global_store_short v[0:1], v2, off offset:64
	v_mul_f32_e32 v2, v40, v72
	v_cvt_pk_bf16_f32 v2, v2, v96
	global_store_short v[0:1], v2, off offset:128
	v_mul_f32_e32 v2, v24, v72
	v_cvt_pk_bf16_f32 v2, v2, v96
	global_store_short v[0:1], v2, off offset:192
	v_mul_f32_e32 v0, v9, v81
	v_cvt_pk_bf16_f32 v2, v0, v96
	v_add_co_u32_e32 v0, vcc, s3, v64
	s_mov_b32 s20, 0x13000
	s_nop 0
	v_addc_co_u32_e32 v1, vcc, 0, v65, vcc
	global_store_short v[0:1], v2, off offset:256
	v_mul_f32_e32 v2, v57, v81
	v_cvt_pk_bf16_f32 v2, v2, v96
	global_store_short v[0:1], v2, off offset:320
	v_mul_f32_e32 v2, v41, v81
	v_cvt_pk_bf16_f32 v2, v2, v96
	global_store_short v[0:1], v2, off offset:384
	v_mul_f32_e32 v2, v25, v81
	v_cvt_pk_bf16_f32 v2, v2, v96
	global_store_short v[0:1], v2, off offset:448
	v_mul_f32_e32 v0, v10, v82
	v_cvt_pk_bf16_f32 v2, v0, v96
	v_add_co_u32_e32 v0, vcc, s20, v64
	s_mov_b32 s20, 0x14000
	s_nop 0
	v_addc_co_u32_e32 v1, vcc, 0, v65, vcc
	global_store_short v[0:1], v2, off offset:512
	v_mul_f32_e32 v2, v58, v82
	v_cvt_pk_bf16_f32 v2, v2, v96
	global_store_short v[0:1], v2, off offset:576
	v_mul_f32_e32 v2, v42, v82
	v_cvt_pk_bf16_f32 v2, v2, v96
	global_store_short v[0:1], v2, off offset:640
	v_mul_f32_e32 v2, v26, v82
	v_cvt_pk_bf16_f32 v2, v2, v96
	global_store_short v[0:1], v2, off offset:704
	v_mul_f32_e32 v0, v11, v83
	v_cvt_pk_bf16_f32 v2, v0, v96
	v_add_co_u32_e32 v0, vcc, s20, v64
	s_waitcnt lgkmcnt(0)
; __device__ __forceinline__ unsigned cvt_pk_bf16(float lo, float hi) { unsigned r; asm volatile("v_cvt_pk_bf16_f32 %0, %1, %2" : "=v"(r) : "v"(lo), "v"(hi)); return r; }
; __device__ __forceinline__ int crow(int r, int hi) { return (r & 3) + 8 * (r >> 2) + 4 * hi; }
; __device__ __forceinline__ void attn_dense_body(const bf16_t* __restrict__ Qb, const bf16_t* __restrict__ Kh, const bf16_t* __restrict__ Vh, bf16_t* __restrict__ Ob, int seq, char* lds) {
;     ...
;   for (int r = 0; r < 16; ++r) rli[r] = __builtin_amdgcn_rcpf(li_l[crow(r, hi)]);
;   bf16_t* Ow = Ob + (long)(wid * QBLK) * LDO;
; #pragma unroll
;   for (int r = 0; r < 16; ++r) { int orow = crow(r, hi);
;     for (int d0 = 0; d0 < 4; ++d0) Ow[(long)orow * LDO + d0 * 32 + r32] = (bf16_t)(cvt_pk_bf16(o[d0][r] * rli[r], 0.f) & 0xffffu); }
	v_rcp_f32_e32 v68, v68
	v_addc_co_u32_e32 v1, vcc, 0, v65, vcc
	global_store_short v[0:1], v2, off offset:768
	v_mul_f32_e32 v2, v59, v83
	v_cvt_pk_bf16_f32 v2, v2, v96
	global_store_short v[0:1], v2, off offset:832
	v_mul_f32_e32 v2, v43, v83
	v_cvt_pk_bf16_f32 v2, v2, v96
	global_store_short v[0:1], v2, off offset:896
	v_mul_f32_e32 v2, v27, v83
	v_cvt_pk_bf16_f32 v2, v2, v96
	global_store_short v[0:1], v2, off offset:960
	v_mul_f32_e32 v0, v12, v68
	s_mov_b32 s20, 0x19000
	v_cvt_pk_bf16_f32 v2, v0, v96
	v_add_co_u32_e32 v0, vcc, s20, v64
	v_rcp_f32_e32 v69, v69
	s_nop 0
	v_addc_co_u32_e32 v1, vcc, 0, v65, vcc
	global_store_short v[0:1], v2, off offset:2048
	v_mul_f32_e32 v2, v60, v68
	v_cvt_pk_bf16_f32 v2, v2, v96
	global_store_short v[0:1], v2, off offset:2112
	v_mul_f32_e32 v2, v44, v68
	v_cvt_pk_bf16_f32 v2, v2, v96
	global_store_short v[0:1], v2, off offset:2176
	v_mul_f32_e32 v2, v28, v68
	v_cvt_pk_bf16_f32 v2, v2, v96
	global_store_short v[0:1], v2, off offset:2240
	v_mul_f32_e32 v0, v13, v69
	s_mov_b32 s20, 0x1a000
	v_cvt_pk_bf16_f32 v2, v0, v96
	v_add_co_u32_e32 v0, vcc, s20, v64
	v_rcp_f32_e32 v70, v70
	s_nop 0
	v_addc_co_u32_e32 v1, vcc, 0, v65, vcc
	global_store_short v[0:1], v2, off offset:2304
	v_mul_f32_e32 v2, v61, v69
	v_cvt_pk_bf16_f32 v2, v2, v96
	global_store_short v[0:1], v2, off offset:2368
	v_mul_f32_e32 v2, v45, v69
	v_cvt_pk_bf16_f32 v2, v2, v96
	global_store_short v[0:1], v2, off offset:2432
	v_mul_f32_e32 v2, v29, v69
	v_cvt_pk_bf16_f32 v2, v2, v96
	global_store_short v[0:1], v2, off offset:2496
	v_mul_f32_e32 v0, v14, v70
	s_mov_b32 s20, 0x1b000
	v_cvt_pk_bf16_f32 v2, v0, v96
	v_add_co_u32_e32 v0, vcc, s20, v64
	v_rcp_f32_e32 v71, v71
	s_nop 0
	v_addc_co_u32_e32 v1, vcc, 0, v65, vcc
	global_store_short v[0:1], v2, off offset:2560
	v_mul_f32_e32 v2, v62, v70
	v_cvt_pk_bf16_f32 v2, v2, v96
	global_store_short v[0:1], v2, off offset:2624
	v_mul_f32_e32 v2, v46, v70
	v_cvt_pk_bf16_f32 v2, v2, v96
	global_store_short v[0:1], v2, off offset:2688
	v_mul_f32_e32 v2, v30, v70
	v_cvt_pk_bf16_f32 v2, v2, v96
	global_store_short v[0:1], v2, off offset:2752
	v_mul_f32_e32 v0, v15, v71
	s_mov_b32 s20, 0x1c000
	v_cvt_pk_bf16_f32 v2, v0, v96
	v_add_co_u32_e32 v0, vcc, s20, v64
	s_mov_b64 s[20:21], 0
	s_nop 0
	v_addc_co_u32_e32 v1, vcc, 0, v65, vcc
	global_store_short v[0:1], v2, off offset:2816
	v_mul_f32_e32 v2, v63, v71
	v_cvt_pk_bf16_f32 v2, v2, v96
	global_store_short v[0:1], v2, off offset:2880
	v_mul_f32_e32 v2, v47, v71
	v_cvt_pk_bf16_f32 v2, v2, v96
	global_store_short v[0:1], v2, off offset:2944
	v_mul_f32_e32 v2, v31, v71
	v_cvt_pk_bf16_f32 v2, v2, v96
	global_store_short v[0:1], v2, off offset:3008

; #define LAS __attribute__((address_space(3)))
; __device__ __forceinline__ int otid() { int t = threadIdx.x; asm volatile("" : "+v"(t)); return t; }
; __device__ __forceinline__ int v_st(int k, int c) { const int kk = (k & ~0xC) | ((k & 4) << 1) | ((k & 8) >> 1); return ((kk >> 3) * 4 + (c >> 5)) * 512 + ((kk & 7) * 32 + (c & 31)) * 2; }
; __device__ __forceinline__ int v_rd_base(int lane) { return ((lane & 3) << 3) | (((lane >> 2) & 3) << 6) | (((lane >> 4) & 1) << 5) | (((lane >> 5) & 1) << 8); }
; #define SLOAD(i, k0) do { sr_[i].vs0 = *reinterpret_cast<const bf16x8*>(&Vh[(long)((k0) + sr) * LDK + sc]); sr_[i].vs1 = *reinterpret_cast<const bf16x8*>(&Vh[(long)((k0) + 32 + sr) * LDK + sc]); \
;     sr_[i].ks0 = *reinterpret_cast<const bf16x8*>(&Kh[(long)((k0) + sr) * LDK + sc]); sr_[i].ks1 = *reinterpret_cast<const bf16x8*>(&Kh[(long)((k0) + 32 + sr) * LDK + sc]); } while (0)
; __device__ __forceinline__ void attn_dense_body(const bf16_t* __restrict__ Qb, const bf16_t* __restrict__ Kh, const bf16_t* __restrict__ Vh, bf16_t* __restrict__ Ob, int seq, char* lds) {
;   const int tid = otid(), wid = tid >> 6, lane = tid & 63, r32 = lane & 31, hi = lane >> 5;
;   bf16_t* V_lds = (bf16_t*)lds; bf16_t* K_lds = (bf16_t*)(lds + 2 * SHM_V);
;   float* ws = (float*)(lds + 2 * SHM_V + 2 * SHM_K) + wid * 64; float* li_l = ws; float* al_l = ws + 32;
;   float m_reg = -1e30f, l_reg = 0; f32x16 o[4] = {}; bf16x8 qr[8];
;   const bf16_t* Qw = Qb + (long)(wid * QBLK + r32) * LDQ + hi * 8;
; #pragma unroll
;   for (int d0 = 0; d0 < 8; ++d0) qr[d0] = *reinterpret_cast<const bf16x8*>(Qw + d0 * 16);
;   const int sr = tid >> 4, sc = (tid & 15) * 8, vst0 = v_st(sr, sc), vst1 = v_st(32 + sr, sc);
;   const int vb0 = (int)(uintptr_t)V_lds + v_rd_base(lane);
;   struct { bf16x8 vs0, vs1, ks0, ks1; } sr_[2];
;     ...
;   f32x16 pA0, pA1, pB0, pB1; float mnA, mnB, alA, alB; bf16x8 pa0, pa1, pa2, pa3; const int NT = seq / KVBLK;
;   constexpr int SE = 0, SO = 1;
;   SLOAD(SE, 0); asm volatile("s_waitcnt vmcnt(0)" ::: "memory"); SWRITE(0, SE); __syncthreads();
; __global__ void __launch_bounds__(512, 2) fwd_megakernel(Params p0) {
;     ...
;                         const int u = *(LAS int*)(lds + LDS_CTL);
;                         if (u >= 64) break;
;                         attn_unit(p, lds_raw, bq * 64 + u);
.LBB0_176:
	s_or_b64 exec, exec, s[20:21]
	v_mov_b32_e32 v0, s62
	s_waitcnt lgkmcnt(0)
	s_barrier
	ds_read_b32 v0, v0
	s_mov_b64 s[20:21], -1
	s_waitcnt lgkmcnt(0)
	v_cmp_lt_i32_e32 vcc, 63, v0
	v_readfirstlane_b32 s22, v0
	s_cbranch_vccnz .LBB0_169
	v_readfirstlane_b32 s32, v190
	s_cmp_lt_u32 s32, 0x100
	s_cbranch_scc1 .Lattn_prio_skip
	s_setprio 1
.Lattn_prio_skip:
	s_add_i32 s20, s22, s51
	s_ashr_i32 s33, s20, 6
	s_lshl_b32 s21, s22, 8
	s_lshl_b32 s20, s33, 11
	s_and_b32 s21, s21, 0x700
	s_or_b32 s46, s20, s21
	s_ashr_i32 s47, s46, 31
	s_bfe_u32 s23, s22, 0x10005
	s_lshl_b64 s[20:21], s[46:47], 11
	s_add_u32 s20, s26, s20
	s_addc_u32 s21, s27, s21
	s_lshl_b32 s22, s22, 4
	s_lshl_b32 s28, s23, 9
	s_and_b32 s22, s22, 0x180
	s_or_b32 s28, s28, s22
	s_lshl_b32 s22, s28, 1
	s_add_u32 s30, s20, s22
	s_addc_u32 s31, s21, 0
	s_mul_i32 s29, s33, 0x120000
	s_mul_hi_i32 s22, s33, 0x120000
	s_add_u32 s20, s24, s29
	s_addc_u32 s21, s25, s22
	s_lshl_b32 s36, s23, 8
	s_add_u32 s20, s20, s36
	v_mov_b32_e32 v74, v190
	s_addc_u32 s21, s21, 0
	s_barrier
	s_add_u32 s23, s40, s29
	v_ashrrev_i32_e32 v16, 4, v74
	s_waitcnt vmcnt(0)
	v_lshlrev_b32_e32 v22, 3, v74
	v_add_u32_e32 v18, 32, v16
	s_addc_u32 s29, s41, s22
	v_and_b32_e32 v0, 0x78, v22
	v_ashrrev_i32_e32 v17, 31, v16
	v_ashrrev_i32_e32 v19, 31, v18
	s_add_u32 s22, s23, s36
	v_lshlrev_b32_e32 v23, 1, v0
	s_waitcnt vmcnt(1)
	v_lshlrev_b64 v[48:49], 9, v[16:17]
	v_lshlrev_b64 v[12:13], 9, v[18:19]
	s_addc_u32 s23, s29, 0
	v_or_b32_e32 v50, v48, v23
	v_mov_b32_e32 v51, v49
	v_or_b32_e32 v12, v12, v23
	v_lshl_add_u64 v[0:1], s[22:23], 0, v[50:51]
	v_lshl_add_u64 v[4:5], s[22:23], 0, v[12:13]
	global_load_dwordx4 v[0:3], v[0:1], off
	s_nop 0
	global_load_dwordx4 v[4:7], v[4:5], off
	v_lshl_add_u64 v[8:9], s[20:21], 0, v[50:51]
	global_load_dwordx4 v[8:11], v[8:9], off
	v_lshl_add_u64 v[12:13], s[20:21], 0, v[12:13]
	s_waitcnt vmcnt(3)
	v_ashrrev_i32_e32 v52, 1, v74
	s_movk_i32 s29, 0xffe0
	global_load_dwordx4 v[12:15], v[12:13], off
	v_bfi_b32 v20, s29, v52, v74
	v_ashrrev_i32_e32 v21, 31, v20
	v_bfe_u32 v97, v74, 5, 1
	v_lshlrev_b64 v[20:21], 11, v[20:21]
	v_lshl_add_u64 v[20:21], s[30:31], 0, v[20:21]
	v_lshlrev_b32_e32 v186, 4, v97
	v_mov_b32_e32 v187, v96
	v_lshl_add_u64 v[20:21], v[20:21], 0, v[186:187]
	global_load_dwordx4 v[118:121], v[20:21], off
	global_load_dwordx4 v[114:117], v[20:21], off offset:32
	global_load_dwordx4 v[126:129], v[20:21], off offset:64
	global_load_dwordx4 v[122:125], v[20:21], off offset:96
	global_load_dwordx4 v[110:113], v[20:21], off offset:128
	global_load_dwordx4 v[106:109], v[20:21], off offset:160
	global_load_dwordx4 v[102:105], v[20:21], off offset:192
	global_load_dwordx4 v[98:101], v[20:21], off offset:224
	v_and_b32_e32 v19, 0xfffff0, v16
	v_lshlrev_b32_e32 v24, 1, v16
	v_lshrrev_b32_e32 v25, 1, v16
	v_and_b32_e32 v26, 3, v16
	v_and_or_b32 v19, v24, 8, v19
	v_and_or_b32 v24, v25, 4, v26
	v_and_b32_e32 v25, 0xfffff0, v18
	v_lshlrev_b32_e32 v26, 1, v18
	v_and_b32_e32 v17, 0x70, v74
	v_bfe_u32 v22, v22, 5, 2
	v_lshlrev_b32_e32 v16, 8, v16
	v_lshrrev_b32_e32 v19, 1, v19
	v_and_or_b32 v25, v26, 8, v25
	v_bitop3_b32 v16, v23, v16, v17 bitop3:0xde
	v_or_b32_e32 v19, v19, v22
	v_lshrrev_b32_e32 v25, 1, v25
	v_lshlrev_b32_e32 v24, 6, v24
	v_and_b32_e32 v27, 48, v23
	v_add_u32_e32 v215, 0, v16
	v_lshlrev_b32_e32 v16, 9, v19
	v_or_b32_e32 v19, v25, v22
	v_or3_b32 v16, v16, v24, v27
	v_lshlrev_b32_e32 v19, 9, v19
	v_or3_b32 v19, v19, v24, v27
	v_add_u32_e32 v216, 0, v16
	v_and_b32_e32 v187, 31, v74
	v_lshlrev_b32_e32 v53, 4, v74
	v_add_u32_e32 v217, 0, v19
	s_waitcnt vmcnt(0)
	v_and_b32_e32 v75, 63, v74
	s_add_i32 s30, 0, 0x10000
	v_and_b32_e32 v209, 0xffffffe0, v52
	s_mov_b64 s[38:39], 0x8000
	v_lshl_add_u64 v[60:61], v[50:51], 0, s[38:39]
	s_mov_b64 s[38:39], 0xc000
	v_lshl_add_u64 v[62:63], v[50:51], 0, s[38:39]
	s_waitcnt vmcnt(11)
	ds_write_b128 v216, v[0:3]
	s_waitcnt vmcnt(10)
	ds_write_b128 v217, v[4:7]
	s_waitcnt vmcnt(9)
	ds_write_b128 v215, v[8:11] offset:32768
	v_lshlrev_b32_e32 v0, 8, v18
	v_bitop3_b32 v0, v23, v0, v17 bitop3:0xde
	v_lshlrev_b32_e32 v8, 8, v187
	v_and_b32_e32 v9, 0x70, v53
	v_add_u32_e32 v218, 0, v0
	v_bitop3_b32 v0, v186, v8, v9 bitop3:0xde
	v_add_u32_e32 v219, 0, v0
	s_waitcnt vmcnt(8)
	ds_write_b128 v218, v[12:15] offset:32768
	s_waitcnt lgkmcnt(0)
	s_barrier
; __device__ __forceinline__ void qkt(f32x16& p0, f32x16& p1, const bf16_t* Ks, const bf16x8* qr, int r32, int hi) {
;   p0 = f32x16{}; p1 = f32x16{};
;   for (int d0 = 0; d0 < 8; ++d0) { int cb = (d0 * 16 + hi * 8) * 2;
;     bf16x8 b0 = *reinterpret_cast<const bf16x8*>((const char*)Ks + KSWZ(r32, cb));
;     bf16x8 b1 = *reinterpret_cast<const bf16x8*>((const char*)Ks + KSWZ(32 + r32, cb));
;     p0 = __builtin_amdgcn_mfma_f32_32x32x16_bf16(b0, qr[d0], p0, 0, 0, 0);
;     p1 = __builtin_amdgcn_mfma_f32_32x32x16_bf16(b1, qr[d0], p1, 0, 0, 0); }
; }
; __device__ __forceinline__ void attn_dense_body(const bf16_t* __restrict__ Qb, const bf16_t* __restrict__ Kh, const bf16_t* __restrict__ Vh, bf16_t* __restrict__ Ob, int seq, char* lds) {
;     ...
;   qkt(pA0, pA1, K_lds, qr, r32, hi); partialSM(pA0, pA1, m_reg, mnA, alA);
	ds_read_b128 v[0:3], v219 offset:32768
	ds_read_b128 v[4:7], v219 offset:40960
	s_waitcnt vmcnt(7) lgkmcnt(1)
	v_mfma_f32_32x32x16_bf16 v[32:47], v[0:3], v[118:121], 0
	v_or_b32_e32 v0, 32, v186
	v_bitop3_b32 v0, v0, v8, v9 bitop3:0xde
	v_add_u32_e32 v226, 0, v0
	v_lshlrev_b32_e32 v10, 3, v75
	v_lshlrev_b32_e32 v12, 1, v74
	v_lshl_add_u64 v[56:57], s[22:23], 0, v[62:63]
	v_lshl_add_u64 v[64:65], s[20:21], 0, v[62:63]
	s_waitcnt lgkmcnt(0)
	v_mfma_f32_32x32x16_bf16 v[16:31], v[4:7], v[118:121], 0
	ds_read_b128 v[0:3], v226 offset:32768
	ds_read_b128 v[4:7], v226 offset:40960
	s_mov_b64 s[38:39], 0x14000
	s_cmp_lg_u32 0, -1
	s_mov_b32 s65, s64
	s_mov_b32 s66, s64
	s_mov_b32 s67, s64
	s_mov_b32 s68, s64
	s_waitcnt vmcnt(6) lgkmcnt(1)
	v_mfma_f32_32x32x16_bf16 v[32:47], v[0:3], v[114:117], v[32:47]
	v_or_b32_e32 v0, 64, v186
	v_bitop3_b32 v0, v0, v8, v9 bitop3:0xde
	v_add_u32_e32 v225, 0, v0
	s_mov_b32 s69, s64
	s_mov_b32 s70, s64
	s_mov_b32 s71, s64
	s_mov_b32 s72, s64
	s_waitcnt lgkmcnt(0)
	v_mfma_f32_32x32x16_bf16 v[16:31], v[4:7], v[114:117], v[16:31]
	ds_read_b128 v[0:3], v225 offset:32768
	ds_read_b128 v[4:7], v225 offset:40960
	s_mov_b32 s73, s64
	s_mov_b32 s74, s64
	s_mov_b32 s75, s64
	s_mov_b32 s76, s64
	s_mov_b32 s77, s64
	s_mov_b32 s78, s64
	s_waitcnt vmcnt(5) lgkmcnt(1)
	v_mfma_f32_32x32x16_bf16 v[32:47], v[0:3], v[126:129], v[32:47]
	v_or_b32_e32 v0, 0x60, v186
	v_bitop3_b32 v0, v0, v8, v9 bitop3:0xde
	v_add_u32_e32 v222, 0, v0
	s_mov_b32 s79, s64
	s_mov_b32 s29, 1
	v_cmp_gt_u32_e64 s[42:43], 32, v75
	v_mov_b32_e32 v212, 0
	s_waitcnt lgkmcnt(0)
	v_mfma_f32_32x32x16_bf16 v[16:31], v[4:7], v[126:129], v[16:31]
	ds_read_b128 v[0:3], v222 offset:32768
	ds_read_b128 v[4:7], v222 offset:40960
	s_waitcnt vmcnt(4) lgkmcnt(1)
	v_mfma_f32_32x32x16_bf16 v[32:47], v[0:3], v[122:125], v[32:47]
	v_or_b32_e32 v0, 0x80, v186
	v_bitop3_b32 v0, v0, v8, v9 bitop3:0xde
	v_add_u32_e32 v221, 0, v0
	s_waitcnt lgkmcnt(0)
	v_mfma_f32_32x32x16_bf16 v[16:31], v[4:7], v[122:125], v[16:31]
	ds_read_b128 v[0:3], v221 offset:32768
	ds_read_b128 v[4:7], v221 offset:40960
	s_waitcnt vmcnt(3) lgkmcnt(1)
	v_mfma_f32_32x32x16_bf16 v[32:47], v[0:3], v[110:113], v[32:47]
	v_or_b32_e32 v0, 0xa0, v186
	v_bitop3_b32 v0, v0, v8, v9 bitop3:0xde
	v_add_u32_e32 v220, 0, v0
	ds_read_b128 v[0:3], v220 offset:32768
	s_waitcnt lgkmcnt(1)
	v_mfma_f32_32x32x16_bf16 v[16:31], v[4:7], v[110:113], v[16:31]
	v_and_b32_e32 v4, 0x3fffffc0, v74
	v_lshl_add_u32 v210, v4, 2, s30
	ds_read_b128 v[4:7], v220 offset:40960
	s_cselect_b32 s30, 0, 0
	v_lshl_add_u32 v211, v187, 2, v210
	s_waitcnt vmcnt(2) lgkmcnt(1)
	v_mfma_f32_32x32x16_bf16 v[32:47], v[0:3], v[106:109], v[32:47]
	v_and_b32_e32 v0, 0xc0, v53
	v_and_or_b32 v11, v10, 24, v0
	v_or_b32_e32 v0, 0xc0, v186
	v_bitop3_b32 v0, v0, v8, v9 bitop3:0xde
	v_add_u32_e32 v223, 0, v0
	ds_read_b128 v[0:3], v223 offset:32768
	s_waitcnt lgkmcnt(1)
	v_mfma_f32_32x32x16_bf16 v[16:31], v[4:7], v[106:109], v[16:31]
	v_and_b32_e32 v4, 32, v12
	v_and_b32_e32 v5, 0x100, v10
	v_or3_b32 v76, v11, v4, v5
	ds_read_b128 v[4:7], v223 offset:40960
	v_add_u32_e32 v214, s30, v76
	s_waitcnt vmcnt(1) lgkmcnt(1)
	v_mfma_f32_32x32x16_bf16 v[32:47], v[0:3], v[102:105], v[32:47]
	v_or_b32_e32 v0, 0xe0, v186
	v_bitop3_b32 v0, v0, v8, v9 bitop3:0xde
	v_add_u32_e32 v224, 0, v0
	ds_read_b128 v[0:3], v224 offset:32768
	ds_read_b128 v[52:55], v224 offset:40960
	s_waitcnt lgkmcnt(2)
	v_mfma_f32_32x32x16_bf16 v[16:31], v[4:7], v[102:105], v[16:31]
	s_waitcnt vmcnt(0) lgkmcnt(1)
	v_mfma_f32_32x32x16_bf16 v[32:47], v[0:3], v[98:101], v[32:47]
	v_mov_b64_e32 v[0:1], s[64:65]
	v_mov_b64_e32 v[14:15], s[78:79]
	v_mov_b64_e32 v[2:3], s[66:67]
	v_mov_b64_e32 v[4:5], s[68:69]
	v_mov_b64_e32 v[6:7], s[70:71]
	v_mov_b64_e32 v[8:9], s[72:73]
	v_mov_b64_e32 v[10:11], s[74:75]
	s_waitcnt lgkmcnt(0)
; #define SLOAD(i, k0) do { sr_[i].vs0 = *reinterpret_cast<const bf16x8*>(&Vh[(long)((k0) + sr) * LDK + sc]); sr_[i].vs1 = *reinterpret_cast<const bf16x8*>(&Vh[(long)((k0) + 32 + sr) * LDK + sc]); \
;     sr_[i].ks0 = *reinterpret_cast<const bf16x8*>(&Kh[(long)((k0) + sr) * LDK + sc]); sr_[i].ks1 = *reinterpret_cast<const bf16x8*>(&Kh[(long)((k0) + 32 + sr) * LDK + sc]); } while (0)
; #define SWRITE(b, i) do { *(bf16x8*)((char*)V_lds + (b) * SHM_V + vst0) = sr_[i].vs0;          \
;     *(bf16x8*)((char*)V_lds + (b) * SHM_V + vst1) = sr_[i].vs1; int kc = sc * 2;               \
;     *(bf16x8*)((char*)K_lds + (b) * SHM_K + KSWZ(sr, kc)) = sr_[i].ks0;                       \
;     *(bf16x8*)((char*)K_lds + (b) * SHM_K + KSWZ(32 + sr, kc)) = sr_[i].ks1; } while (0)
; #define SWAIT() asm volatile("s_waitcnt vmcnt(4)" ::: "memory")
; __device__ __forceinline__ void partialSM(f32x16& p0, f32x16& p1, float& m_reg, float& mn, float& alpha) {
;   constexpr float C = SCALE * 1.4426950408889634f;
;   float pmax = p0[0]; for (int r = 1; r < 16; ++r) pmax = fmaxf(pmax, p0[r]); for (int r = 0; r < 16; ++r) pmax = fmaxf(pmax, p1[r]);
;   { auto rr = __builtin_amdgcn_permlane32_swap(__float_as_uint(pmax), __float_as_uint(pmax), false, false);
;     pmax = fmaxf(__uint_as_float(rr[0]), __uint_as_float(rr[1])); }
;   if (__builtin_expect(__all(pmax - m_reg <= THR / SCALE), 1)) { mn = m_reg; alpha = 1.f; }
;   else { mn = fmaxf(m_reg, pmax); alpha = __builtin_amdgcn_exp2f((m_reg - mn) * C); m_reg = mn; }
;   float mnC = -mn * C;
;   for (int r = 0; r < 16; ++r) p0[r] = fmaf(p0[r], C, mnC); for (int r = 0; r < 16; ++r) p1[r] = fmaf(p1[r], C, mnC);
;   for (int r = 0; r < 16; ++r) p0[r] = __builtin_amdgcn_exp2f(p0[r]);
; }
; __device__ __forceinline__ void attn_dense_body(const bf16_t* __restrict__ Qb, const bf16_t* __restrict__ Kh, const bf16_t* __restrict__ Vh, bf16_t* __restrict__ Ob, int seq, char* lds) {
;     ...
;   qkt(pA0, pA1, K_lds, qr, r32, hi); partialSM(pA0, pA1, m_reg, mnA, alA);
;   SLOAD(SO, KVBLK); if (2 < NT) SLOAD(SE, 2 * KVBLK);
;   SWAIT(); SWRITE(1, SO); __syncthreads();
	v_mfma_f32_32x32x16_bf16 v[16:31], v[52:55], v[98:101], v[16:31]
	s_nop 2
	v_max_f32_e32 v52, v33, v33
	v_max_f32_e32 v53, v32, v32
	v_max_f32_e32 v52, v53, v52
	v_max3_f32 v52, v52, v34, v35
	v_max3_f32 v52, v52, v36, v37
	v_max3_f32 v52, v52, v38, v39
	v_max3_f32 v52, v52, v40, v41
	v_max3_f32 v52, v52, v42, v43
	v_max3_f32 v52, v52, v44, v45
	v_max3_f32 v52, v52, v46, v47
	v_max3_f32 v68, v52, v16, v17
	v_max3_f32 v68, v68, v18, v19
	v_max3_f32 v68, v68, v20, v21
	v_max3_f32 v68, v68, v22, v23
	v_max3_f32 v68, v68, v24, v25
	v_max3_f32 v68, v68, v26, v27
	v_lshl_add_u64 v[52:53], s[22:23], 0, v[60:61]
	v_lshl_add_u64 v[60:61], s[20:21], 0, v[60:61]
	v_max3_f32 v68, v68, v28, v29
	global_load_dwordx4 v[52:55], v[52:53], off
	s_nop 0
	global_load_dwordx4 v[56:59], v[56:57], off
	s_nop 0
	global_load_dwordx4 v[60:63], v[60:61], off
	s_nop 0
	global_load_dwordx4 v[64:67], v[64:65], off
	v_max3_f32 v77, v68, v30, v31
	v_lshl_add_u64 v[68:69], v[50:51], 0, s[38:39]
	v_lshl_add_u64 v[70:71], s[20:21], 0, v[68:69]
	v_lshl_add_u64 v[50:51], v[50:51], 0, s[34:35]
	v_lshl_add_u64 v[68:69], s[22:23], 0, v[68:69]
	v_lshl_add_u64 v[72:73], s[20:21], 0, v[50:51]
	global_load_dwordx4 v[138:141], v[70:71], off
	global_load_dwordx4 v[130:133], v[72:73], off
	v_lshl_add_u64 v[50:51], s[22:23], 0, v[50:51]
	global_load_dwordx4 v[142:145], v[68:69], off
	global_load_dwordx4 v[134:137], v[50:51], off
	v_mov_b32_e32 v78, v77
	s_nop 1
	v_permlane32_swap_b32_e32 v77, v78
	v_max_f32_e32 v50, v78, v78
	v_max_f32_e32 v51, v77, v77
	v_max_f32_e32 v50, v51, v50
	v_add_f32_e32 v51, 0x7149f2ca, v50
	v_max_f32_e32 v50, 0xf149f2ca, v50
	v_cmp_ge_f32_e32 vcc, s63, v51
	v_sub_f32_e32 v51, 0xf149f2ca, v50
	v_mul_f32_e32 v51, 0x3e0293ee, v51
	v_exp_f32_e32 v51, v51
	s_cmp_eq_u64 vcc, exec
	s_cselect_b64 vcc, -1, 0
	v_mov_b32_e32 v68, 0xf149f2ca
	v_cndmask_b32_e32 v170, v50, v68, vcc
	v_mul_f32_e32 v50, 0xbe0293ee, v170
	v_cndmask_b32_e64 v227, v51, 1.0, vcc
	v_mov_b32_e32 v51, v50
	v_fmac_f32_e32 v51, 0x3e0293ee, v47
	v_fmamk_f32 v32, v32, 0x3e0293ee, v50
	v_fmamk_f32 v33, v33, 0x3e0293ee, v50
	v_fmamk_f32 v34, v34, 0x3e0293ee, v50
	v_fmamk_f32 v35, v35, 0x3e0293ee, v50
	v_fmamk_f32 v36, v36, 0x3e0293ee, v50
	v_fmamk_f32 v37, v37, 0x3e0293ee, v50
	v_fmamk_f32 v38, v38, 0x3e0293ee, v50
	v_fmamk_f32 v39, v39, 0x3e0293ee, v50
	v_fmamk_f32 v40, v40, 0x3e0293ee, v50
	v_fmamk_f32 v41, v41, 0x3e0293ee, v50
	v_fmamk_f32 v42, v42, 0x3e0293ee, v50
	v_fmamk_f32 v43, v43, 0x3e0293ee, v50
	v_fmamk_f32 v44, v44, 0x3e0293ee, v50
	v_fmamk_f32 v45, v45, 0x3e0293ee, v50
	v_fmamk_f32 v46, v46, 0x3e0293ee, v50
	v_pk_fma_f32 v[156:157], v[18:19], s[96:97], v[50:51] op_sel_hi:[1,0,0]
	v_pk_fma_f32 v[158:159], v[16:17], s[96:97], v[50:51] op_sel_hi:[1,0,0]
	v_mov_b32_e32 v16, 0x120000
	v_and_b32_e32 v18, 15, v74
	v_exp_f32_e32 v177, v32
	v_exp_f32_e32 v234, v33
	v_exp_f32_e32 v163, v34
	v_exp_f32_e32 v231, v35
	v_exp_f32_e32 v164, v36
	v_exp_f32_e32 v176, v37
	v_exp_f32_e32 v165, v38
	v_exp_f32_e32 v175, v39
	v_exp_f32_e32 v166, v40
	v_exp_f32_e32 v174, v41
	v_exp_f32_e32 v167, v42
	v_exp_f32_e32 v173, v43
	v_exp_f32_e32 v168, v44
	v_exp_f32_e32 v172, v45
	v_exp_f32_e32 v169, v46
	v_exp_f32_e32 v171, v51
	v_mad_i64_i32 v[16:17], s[20:21], s33, v16, v[48:49]
	v_lshlrev_b32_e32 v18, 4, v18
	s_waitcnt vmcnt(4)
	v_or3_b32 v16, v16, s36, v18
	v_mov_b64_e32 v[12:13], s[76:77]
	v_pk_fma_f32 v[152:153], v[30:31], s[96:97], v[50:51] op_sel_hi:[1,0,0]
	v_pk_fma_f32 v[154:155], v[28:29], s[96:97], v[50:51] op_sel_hi:[1,0,0]
	v_pk_fma_f32 v[160:161], v[26:27], s[96:97], v[50:51] op_sel_hi:[1,0,0]
	v_pk_fma_f32 v[146:147], v[24:25], s[96:97], v[50:51] op_sel_hi:[1,0,0]
	v_pk_fma_f32 v[148:149], v[22:23], s[96:97], v[50:51] op_sel_hi:[1,0,0]
	v_pk_fma_f32 v[150:151], v[20:21], s[96:97], v[50:51] op_sel_hi:[1,0,0]
	s_waitcnt vmcnt(7)
	ds_write_b128 v216, v[52:55] offset:16384
	s_waitcnt vmcnt(6)
	ds_write_b128 v217, v[56:59] offset:16384
	s_waitcnt vmcnt(5)
	ds_write_b128 v215, v[60:63] offset:49152
	s_waitcnt vmcnt(4)
	ds_write_b128 v218, v[64:67] offset:49152
	s_addk_i32 s30, 0x4000
	v_lshl_add_u64 v[188:189], s[16:17], 0, v[16:17]
	v_mov_b64_e32 v[62:63], v[14:15]
	v_mov_b64_e32 v[46:47], v[14:15]
	v_mov_b64_e32 v[30:31], v[14:15]
	v_add_u32_e32 v213, s30, v76
	v_mov_b64_e32 v[60:61], v[12:13]
	v_mov_b64_e32 v[58:59], v[10:11]
	v_mov_b64_e32 v[56:57], v[8:9]
	v_mov_b64_e32 v[54:55], v[6:7]
	v_mov_b64_e32 v[52:53], v[4:5]
	v_mov_b64_e32 v[50:51], v[2:3]
	v_mov_b64_e32 v[48:49], v[0:1]
	v_mov_b64_e32 v[44:45], v[12:13]
	v_mov_b64_e32 v[42:43], v[10:11]
	v_mov_b64_e32 v[40:41], v[8:9]
	v_mov_b64_e32 v[38:39], v[6:7]
	v_mov_b64_e32 v[36:37], v[4:5]
	v_mov_b64_e32 v[34:35], v[2:3]
	v_mov_b64_e32 v[32:33], v[0:1]
	v_mov_b64_e32 v[28:29], v[12:13]
	v_mov_b64_e32 v[26:27], v[10:11]
	v_mov_b64_e32 v[24:25], v[8:9]
	v_mov_b64_e32 v[22:23], v[6:7]
	v_mov_b64_e32 v[20:21], v[4:5]
	v_mov_b64_e32 v[18:19], v[2:3]
	v_mov_b64_e32 v[16:17], v[0:1]
	s_waitcnt lgkmcnt(0)
	s_barrier
